# P7 SwiGLU epilogue: scalar v_mul/v_fma runs replaced by in-place v_pk_mul_f32/v_pk_fma_f32 with broadcast op_sel (bit-identical)
# baseline (speedup 1.0000x reference)
.LBB0_1467:
	v_lshl_add_u32 v138, s28, 8, v140
	v_ashrrev_i32_e32 v139, 31, v138
	v_lshlrev_b64 v[176:177], 6, v[138:139]
	v_lshl_add_u64 v[176:177], s[8:9], 0, v[176:177]
	v_and_b32_e32 v178, 48, v188
	v_mov_b32_e32 v179, 0
	s_mov_b64 s[98:99], 0x2000
	v_lshl_add_u64 v[176:177], v[176:177], 0, v[178:179]
	v_lshl_add_u64 v[178:179], v[176:177], 0, s[98:99]
	global_load_dwordx4 v[180:183], v[176:177], off
	global_load_dwordx4 v[184:187], v[176:177], off offset:1024
	global_load_dwordx4 v[192:195], v[176:177], off offset:2048
	global_load_dwordx4 v[196:199], v[176:177], off offset:3072
	global_load_dwordx4 v[200:203], v[178:179], off
	global_load_dwordx4 v[204:207], v[178:179], off offset:1024
	global_load_dwordx4 v[208:211], v[178:179], off offset:2048
	global_load_dwordx4 v[212:215], v[178:179], off offset:3072
	v_and_b32_e32 v174, 15, v188
	v_lshlrev_b32_e32 v216, 2, v174
	v_add_u32_e32 v217, 64, v216
	v_add_u32_e32 v218, 128, v216
	v_add_u32_e32 v219, 192, v216
	v_lshlrev_b64 v[148:149], 6, v[138:139]
	v_lshl_add_u64 v[160:161], s[8:9], 0, v[148:149]
	v_lshl_or_b32 v164, s26, 7, v142
	v_ashrrev_i32_e32 v165, 31, v164
	v_pk_mul_f32 v[166:167], v[122:123], v[114:115]
	v_lshlrev_b64 v[122:123], 1, v[164:165]
	v_pk_mul_f32 v[126:127], v[126:127], v[118:119]
	v_pk_mul_f32 v[124:125], v[124:125], v[116:117]
	v_pk_mul_f32 v[168:169], v[120:121], v[112:113]
	v_mov_b64_e32 v[120:121], s[10:11]
	v_or_b32_e32 v172, 16, v138
	v_mad_i64_i32 v[170:171], s[4:5], v138, s55, v[120:121]
	v_ashrrev_i32_e32 v173, 31, v172
	v_pk_mul_f32 v[110:111], v[110:111], v[102:103]
	v_pk_mul_f32 v[108:109], v[108:109], v[100:101]
	v_pk_mul_f32 v[106:107], v[106:107], v[98:99]
	v_pk_mul_f32 v[104:105], v[104:105], v[96:97]
	v_pk_mul_f32 v[94:95], v[94:95], v[86:87]
	v_pk_mul_f32 v[92:93], v[92:93], v[84:85]
	v_pk_mul_f32 v[90:91], v[90:91], v[82:83]
	v_pk_mul_f32 v[88:89], v[88:89], v[80:81]
	v_pk_mul_f32 v[78:79], v[78:79], v[70:71]
	v_pk_mul_f32 v[76:77], v[76:77], v[68:69]
	v_pk_mul_f32 v[74:75], v[74:75], v[66:67]
	v_pk_mul_f32 v[72:73], v[72:73], v[64:65]
	v_pk_mul_f32 v[62:63], v[62:63], v[54:55]
	v_pk_mul_f32 v[60:61], v[60:61], v[52:53]
	v_pk_mul_f32 v[58:59], v[58:59], v[50:51]
	v_pk_mul_f32 v[56:57], v[56:57], v[48:49]
	v_pk_mul_f32 v[46:47], v[46:47], v[38:39]
	v_pk_mul_f32 v[44:45], v[44:45], v[36:37]
	v_pk_mul_f32 v[42:43], v[42:43], v[34:35]
	v_pk_mul_f32 v[40:41], v[40:41], v[32:33]
	v_pk_mul_f32 v[30:31], v[30:31], v[22:23]
	v_pk_mul_f32 v[28:29], v[28:29], v[20:21]
	v_pk_mul_f32 v[26:27], v[26:27], v[18:19]
	v_pk_mul_f32 v[24:25], v[24:25], v[16:17]
	v_pk_mul_f32 v[14:15], v[14:15], v[6:7]
	v_pk_mul_f32 v[12:13], v[12:13], v[4:5]
	v_pk_mul_f32 v[10:11], v[10:11], v[2:3]
	v_pk_mul_f32 v[8:9], v[8:9], v[0:1]
	s_cmp_eq_u32 s45, s49
	s_waitcnt vmcnt(0)
	v_add_f32_e32 v180, v180, v181
	v_add_f32_e32 v182, v182, v183
	v_add_f32_e32 v184, v184, v185
	v_add_f32_e32 v186, v186, v187
	v_add_f32_e32 v192, v192, v193
	v_add_f32_e32 v194, v194, v195
	v_add_f32_e32 v196, v196, v197
	v_add_f32_e32 v198, v198, v199
	v_add_f32_e32 v200, v200, v201
	v_add_f32_e32 v202, v202, v203
	v_add_f32_e32 v204, v204, v205
	v_add_f32_e32 v206, v206, v207
	v_add_f32_e32 v208, v208, v209
	v_add_f32_e32 v210, v210, v211
	v_add_f32_e32 v212, v212, v213
	v_add_f32_e32 v214, v214, v215
	v_add_f32_e32 v180, v180, v182
	v_add_f32_e32 v184, v184, v186
	v_add_f32_e32 v192, v192, v194
	v_add_f32_e32 v196, v196, v198
	v_add_f32_e32 v200, v200, v202
	v_add_f32_e32 v204, v204, v206
	v_add_f32_e32 v208, v208, v210
	v_add_f32_e32 v212, v212, v214
	ds_bpermute_b32 v181, v216, v180
	ds_bpermute_b32 v185, v216, v184
	ds_bpermute_b32 v193, v216, v192
	ds_bpermute_b32 v197, v216, v196
	ds_bpermute_b32 v201, v216, v200
	ds_bpermute_b32 v205, v216, v204
	ds_bpermute_b32 v209, v216, v208
	ds_bpermute_b32 v213, v216, v212
	s_waitcnt lgkmcnt(0)
	ds_bpermute_b32 v182, v217, v180
	ds_bpermute_b32 v186, v217, v184
	ds_bpermute_b32 v194, v217, v192
	ds_bpermute_b32 v198, v217, v196
	ds_bpermute_b32 v202, v217, v200
	ds_bpermute_b32 v206, v217, v204
	ds_bpermute_b32 v210, v217, v208
	ds_bpermute_b32 v214, v217, v212
	s_waitcnt lgkmcnt(0)
	v_add_f32_e32 v181, v181, v182
	v_add_f32_e32 v185, v185, v186
	v_add_f32_e32 v193, v193, v194
	v_add_f32_e32 v197, v197, v198
	v_add_f32_e32 v201, v201, v202
	v_add_f32_e32 v205, v205, v206
	v_add_f32_e32 v209, v209, v210
	v_add_f32_e32 v213, v213, v214
	ds_bpermute_b32 v182, v218, v180
	ds_bpermute_b32 v186, v218, v184
	ds_bpermute_b32 v194, v218, v192
	ds_bpermute_b32 v198, v218, v196
	ds_bpermute_b32 v202, v218, v200
	ds_bpermute_b32 v206, v218, v204
	ds_bpermute_b32 v210, v218, v208
	ds_bpermute_b32 v214, v218, v212
	s_waitcnt lgkmcnt(0)
	v_add_f32_e32 v181, v181, v182
	v_add_f32_e32 v185, v185, v186
	v_add_f32_e32 v193, v193, v194
	v_add_f32_e32 v197, v197, v198
	v_add_f32_e32 v201, v201, v202
	v_add_f32_e32 v205, v205, v206
	v_add_f32_e32 v209, v209, v210
	v_add_f32_e32 v213, v213, v214
	ds_bpermute_b32 v182, v219, v180
	ds_bpermute_b32 v186, v219, v184
	ds_bpermute_b32 v194, v219, v192
	ds_bpermute_b32 v198, v219, v196
	ds_bpermute_b32 v202, v219, v200
	ds_bpermute_b32 v206, v219, v204
	ds_bpermute_b32 v210, v219, v208
	ds_bpermute_b32 v214, v219, v212
	s_waitcnt lgkmcnt(0)
	v_add_f32_e32 v181, v181, v182
	v_add_f32_e32 v185, v185, v186
	v_add_f32_e32 v193, v193, v194
	v_add_f32_e32 v197, v197, v198
	v_add_f32_e32 v201, v201, v202
	v_add_f32_e32 v205, v205, v206
	v_add_f32_e32 v209, v209, v210
	v_add_f32_e32 v213, v213, v214
	v_lshlrev_b64 v[150:151], 6, v[172:173]
	v_lshl_add_u64 v[150:151], s[8:9], 0, v[150:151]
	v_fmamk_f32 v139, v181, 0x3a800000, v146
	v_lshl_add_u64 v[148:149], v[170:171], 0, v[122:123]
	v_mad_i64_i32 v[154:155], s[4:5], v172, s55, v[120:121]
	v_rsq_f32_e32 v139, v139
	s_nop 0
	v_mul_f32_e32 v147, 0xbfb8aa3b, v139
	v_mul_f32_e32 v139, v139, v139
	v_pk_mul_f32 v[116:117], v[116:117], v[146:147] op_sel:[0,1]
	v_pk_mul_f32 v[118:119], v[118:119], v[146:147] op_sel:[0,1]
	v_pk_mul_f32 v[112:113], v[112:113], v[146:147] op_sel:[0,1]
	v_pk_mul_f32 v[114:115], v[114:115], v[146:147] op_sel:[0,1]
	v_rcp_f32_e32 v139, v139
	v_exp_f32_e32 v116, v116
	v_exp_f32_e32 v117, v117
	v_exp_f32_e32 v118, v118
	v_exp_f32_e32 v119, v119
	v_exp_f32_e32 v112, v112
	v_exp_f32_e32 v113, v113
	v_exp_f32_e32 v114, v114
	v_exp_f32_e32 v115, v115
	v_pk_fma_f32 v[116:117], v[116:117], v[138:139], v[138:139] op_sel:[0,1,1]
	v_pk_fma_f32 v[118:119], v[118:119], v[138:139], v[138:139] op_sel:[0,1,1]
	v_pk_fma_f32 v[112:113], v[112:113], v[138:139], v[138:139] op_sel:[0,1,1]
	v_pk_fma_f32 v[114:115], v[114:115], v[138:139], v[138:139] op_sel:[0,1,1]
	v_rcp_f32_e32 v116, v116
	v_rcp_f32_e32 v117, v117
	v_rcp_f32_e32 v118, v118
	v_rcp_f32_e32 v119, v119
	v_rcp_f32_e32 v112, v112
	v_rcp_f32_e32 v113, v113
	v_rcp_f32_e32 v114, v114
	v_rcp_f32_e32 v115, v115
	v_pk_mul_f32 v[116:117], v[124:125], v[116:117]
	v_pk_mul_f32 v[118:119], v[126:127], v[118:119]
	v_pk_mul_f32 v[112:113], v[168:169], v[112:113]
	v_pk_mul_f32 v[114:115], v[166:167], v[114:115]
	v_cvt_pk_bf16_f32 v116, v116, v117
	v_cvt_pk_bf16_f32 v117, v118, v119
	v_cvt_pk_bf16_f32 v118, v112, v113
	v_cvt_pk_bf16_f32 v119, v114, v115
	global_store_dwordx4 v[148:149], v[116:119], off
	v_or_b32_e32 v152, 32, v138
	v_ashrrev_i32_e32 v153, 31, v152
	v_fmamk_f32 v112, v185, 0x3a800000, v146
	v_rsq_f32_e32 v116, v112
	v_lshl_add_u64 v[112:113], v[154:155], 0, v[122:123]
	v_mul_f32_e32 v117, 0xbfb8aa3b, v116
	v_mul_f32_e32 v116, v116, v116
	v_pk_mul_f32 v[100:101], v[100:101], v[116:117] op_sel:[0,1]
	v_pk_mul_f32 v[102:103], v[102:103], v[116:117] op_sel:[0,1]
	v_pk_mul_f32 v[96:97], v[96:97], v[116:117] op_sel:[0,1]
	v_pk_mul_f32 v[98:99], v[98:99], v[116:117] op_sel:[0,1]
	v_rcp_f32_e32 v116, v116
	v_exp_f32_e32 v100, v100
	v_exp_f32_e32 v101, v101
	v_exp_f32_e32 v102, v102
	v_exp_f32_e32 v103, v103
	v_exp_f32_e32 v96, v96
	v_exp_f32_e32 v97, v97
	v_exp_f32_e32 v98, v98
	v_exp_f32_e32 v99, v99
	v_pk_fma_f32 v[100:101], v[100:101], v[116:117], v[116:117] op_sel_hi:[1,0,0]
	v_pk_fma_f32 v[102:103], v[102:103], v[116:117], v[116:117] op_sel_hi:[1,0,0]
	v_pk_fma_f32 v[96:97], v[96:97], v[116:117], v[116:117] op_sel_hi:[1,0,0]
	v_pk_fma_f32 v[98:99], v[98:99], v[116:117], v[116:117] op_sel_hi:[1,0,0]
	v_rcp_f32_e32 v100, v100
	v_rcp_f32_e32 v101, v101
	v_rcp_f32_e32 v102, v102
	v_rcp_f32_e32 v103, v103
	v_rcp_f32_e32 v96, v96
	v_rcp_f32_e32 v97, v97
	v_rcp_f32_e32 v98, v98
	v_rcp_f32_e32 v99, v99
	v_pk_mul_f32 v[100:101], v[108:109], v[100:101]
	v_pk_mul_f32 v[102:103], v[110:111], v[102:103]
	v_pk_mul_f32 v[96:97], v[104:105], v[96:97]
	v_pk_mul_f32 v[98:99], v[106:107], v[98:99]
	v_cvt_pk_bf16_f32 v100, v100, v101
	v_cvt_pk_bf16_f32 v101, v102, v103
	v_cvt_pk_bf16_f32 v102, v96, v97
	v_cvt_pk_bf16_f32 v103, v98, v99
	global_store_dwordx4 v[112:113], v[100:103], off
	v_or_b32_e32 v112, 48, v138
	v_mad_i64_i32 v[114:115], s[4:5], v152, s55, v[120:121]
	v_ashrrev_i32_e32 v113, 31, v112
	v_fmamk_f32 v96, v193, 0x3a800000, v146
	v_rsq_f32_e32 v100, v96
	v_lshl_add_u64 v[96:97], v[114:115], 0, v[122:123]
	v_mul_f32_e32 v101, 0xbfb8aa3b, v100
	v_mul_f32_e32 v100, v100, v100
	v_pk_mul_f32 v[84:85], v[84:85], v[100:101] op_sel:[0,1]
	v_pk_mul_f32 v[86:87], v[86:87], v[100:101] op_sel:[0,1]
	v_pk_mul_f32 v[80:81], v[80:81], v[100:101] op_sel:[0,1]
	v_pk_mul_f32 v[82:83], v[82:83], v[100:101] op_sel:[0,1]
	v_rcp_f32_e32 v100, v100
	v_exp_f32_e32 v84, v84
	v_exp_f32_e32 v85, v85
	v_exp_f32_e32 v86, v86
	v_exp_f32_e32 v87, v87
	v_exp_f32_e32 v80, v80
	v_exp_f32_e32 v81, v81
	v_exp_f32_e32 v82, v82
	v_exp_f32_e32 v83, v83
	v_pk_fma_f32 v[84:85], v[84:85], v[100:101], v[100:101] op_sel_hi:[1,0,0]
	v_pk_fma_f32 v[86:87], v[86:87], v[100:101], v[100:101] op_sel_hi:[1,0,0]
	v_pk_fma_f32 v[80:81], v[80:81], v[100:101], v[100:101] op_sel_hi:[1,0,0]
	v_pk_fma_f32 v[82:83], v[82:83], v[100:101], v[100:101] op_sel_hi:[1,0,0]
	v_rcp_f32_e32 v84, v84
	v_rcp_f32_e32 v85, v85
	v_rcp_f32_e32 v86, v86
	v_rcp_f32_e32 v87, v87
	v_rcp_f32_e32 v80, v80
	v_rcp_f32_e32 v81, v81
	v_rcp_f32_e32 v82, v82
	v_rcp_f32_e32 v83, v83
	v_pk_mul_f32 v[84:85], v[92:93], v[84:85]
	v_pk_mul_f32 v[86:87], v[94:95], v[86:87]
	v_pk_mul_f32 v[80:81], v[88:89], v[80:81]
	v_pk_mul_f32 v[82:83], v[90:91], v[82:83]
	v_cvt_pk_bf16_f32 v84, v84, v85
	v_cvt_pk_bf16_f32 v85, v86, v87
	v_cvt_pk_bf16_f32 v86, v80, v81
	v_cvt_pk_bf16_f32 v87, v82, v83
	global_store_dwordx4 v[96:97], v[84:87], off
	v_add_u32_e32 v96, 0x80, v138
	v_mad_i64_i32 v[98:99], s[4:5], v112, s55, v[120:121]
	v_ashrrev_i32_e32 v97, 31, v96
	v_fmamk_f32 v80, v197, 0x3a800000, v146
	v_rsq_f32_e32 v84, v80
	v_lshl_add_u64 v[80:81], v[98:99], 0, v[122:123]
	v_mul_f32_e32 v85, 0xbfb8aa3b, v84
	v_mul_f32_e32 v84, v84, v84
	v_pk_mul_f32 v[68:69], v[68:69], v[84:85] op_sel:[0,1]
	v_pk_mul_f32 v[70:71], v[70:71], v[84:85] op_sel:[0,1]
	v_pk_mul_f32 v[64:65], v[64:65], v[84:85] op_sel:[0,1]
	v_pk_mul_f32 v[66:67], v[66:67], v[84:85] op_sel:[0,1]
	v_rcp_f32_e32 v84, v84
	v_exp_f32_e32 v68, v68
	v_exp_f32_e32 v69, v69
	v_exp_f32_e32 v70, v70
	v_exp_f32_e32 v71, v71
	v_exp_f32_e32 v64, v64
	v_exp_f32_e32 v65, v65
	v_exp_f32_e32 v66, v66
	v_exp_f32_e32 v67, v67
	v_pk_fma_f32 v[68:69], v[68:69], v[84:85], v[84:85] op_sel_hi:[1,0,0]
	v_pk_fma_f32 v[70:71], v[70:71], v[84:85], v[84:85] op_sel_hi:[1,0,0]
	v_pk_fma_f32 v[64:65], v[64:65], v[84:85], v[84:85] op_sel_hi:[1,0,0]
	v_pk_fma_f32 v[66:67], v[66:67], v[84:85], v[84:85] op_sel_hi:[1,0,0]
	v_rcp_f32_e32 v68, v68
	v_rcp_f32_e32 v69, v69
	v_rcp_f32_e32 v70, v70
	v_rcp_f32_e32 v71, v71
	v_rcp_f32_e32 v64, v64
	v_rcp_f32_e32 v65, v65
	v_rcp_f32_e32 v66, v66
	v_rcp_f32_e32 v67, v67
	v_pk_mul_f32 v[68:69], v[76:77], v[68:69]
	v_pk_mul_f32 v[70:71], v[78:79], v[70:71]
	v_pk_mul_f32 v[64:65], v[72:73], v[64:65]
	v_pk_mul_f32 v[66:67], v[74:75], v[66:67]
	v_cvt_pk_bf16_f32 v68, v68, v69
	v_cvt_pk_bf16_f32 v69, v70, v71
	v_cvt_pk_bf16_f32 v70, v64, v65
	v_cvt_pk_bf16_f32 v71, v66, v67
	global_store_dwordx4 v[80:81], v[68:71], off
	v_add_u32_e32 v80, 0x90, v138
	v_mad_i64_i32 v[82:83], s[4:5], v96, s55, v[120:121]
	v_ashrrev_i32_e32 v81, 31, v80
	v_fmamk_f32 v64, v201, 0x3a800000, v146
	v_rsq_f32_e32 v68, v64
	v_lshl_add_u64 v[64:65], v[82:83], 0, v[122:123]
	v_mul_f32_e32 v69, 0xbfb8aa3b, v68
	v_mul_f32_e32 v68, v68, v68
	v_pk_mul_f32 v[52:53], v[52:53], v[68:69] op_sel:[0,1]
	v_pk_mul_f32 v[54:55], v[54:55], v[68:69] op_sel:[0,1]
	v_pk_mul_f32 v[48:49], v[48:49], v[68:69] op_sel:[0,1]
	v_pk_mul_f32 v[50:51], v[50:51], v[68:69] op_sel:[0,1]
	v_rcp_f32_e32 v68, v68
	v_exp_f32_e32 v52, v52
	v_exp_f32_e32 v53, v53
	v_exp_f32_e32 v54, v54
	v_exp_f32_e32 v55, v55
	v_exp_f32_e32 v48, v48
	v_exp_f32_e32 v49, v49
	v_exp_f32_e32 v50, v50
	v_exp_f32_e32 v51, v51
	v_pk_fma_f32 v[52:53], v[52:53], v[68:69], v[68:69] op_sel_hi:[1,0,0]
	v_pk_fma_f32 v[54:55], v[54:55], v[68:69], v[68:69] op_sel_hi:[1,0,0]
	v_pk_fma_f32 v[48:49], v[48:49], v[68:69], v[68:69] op_sel_hi:[1,0,0]
	v_pk_fma_f32 v[50:51], v[50:51], v[68:69], v[68:69] op_sel_hi:[1,0,0]
	v_rcp_f32_e32 v52, v52
	v_rcp_f32_e32 v53, v53
	v_rcp_f32_e32 v54, v54
	v_rcp_f32_e32 v55, v55
	v_rcp_f32_e32 v48, v48
	v_rcp_f32_e32 v49, v49
	v_rcp_f32_e32 v50, v50
	v_rcp_f32_e32 v51, v51
	v_pk_mul_f32 v[52:53], v[60:61], v[52:53]
	v_pk_mul_f32 v[54:55], v[62:63], v[54:55]
	v_pk_mul_f32 v[48:49], v[56:57], v[48:49]
	v_pk_mul_f32 v[50:51], v[58:59], v[50:51]
	v_cvt_pk_bf16_f32 v52, v52, v53
	v_cvt_pk_bf16_f32 v53, v54, v55
	v_cvt_pk_bf16_f32 v54, v48, v49
	v_cvt_pk_bf16_f32 v55, v50, v51
	global_store_dwordx4 v[64:65], v[52:55], off
	v_add_u32_e32 v64, 0xa0, v138
	v_mad_i64_i32 v[66:67], s[4:5], v80, s55, v[120:121]
	v_ashrrev_i32_e32 v65, 31, v64
	v_fmamk_f32 v48, v205, 0x3a800000, v146
	v_rsq_f32_e32 v52, v48
	v_lshl_add_u64 v[48:49], v[66:67], 0, v[122:123]
	v_mul_f32_e32 v53, 0xbfb8aa3b, v52
	v_mul_f32_e32 v52, v52, v52
	v_pk_mul_f32 v[36:37], v[36:37], v[52:53] op_sel:[0,1]
	v_pk_mul_f32 v[38:39], v[38:39], v[52:53] op_sel:[0,1]
	v_pk_mul_f32 v[32:33], v[32:33], v[52:53] op_sel:[0,1]
	v_pk_mul_f32 v[34:35], v[34:35], v[52:53] op_sel:[0,1]
	v_rcp_f32_e32 v52, v52
	v_exp_f32_e32 v36, v36
	v_exp_f32_e32 v37, v37
	v_exp_f32_e32 v38, v38
	v_exp_f32_e32 v39, v39
	v_exp_f32_e32 v32, v32
	v_exp_f32_e32 v33, v33
	v_exp_f32_e32 v34, v34
	v_exp_f32_e32 v35, v35
	v_pk_fma_f32 v[36:37], v[36:37], v[52:53], v[52:53] op_sel_hi:[1,0,0]
	v_pk_fma_f32 v[38:39], v[38:39], v[52:53], v[52:53] op_sel_hi:[1,0,0]
	v_pk_fma_f32 v[32:33], v[32:33], v[52:53], v[52:53] op_sel_hi:[1,0,0]
	v_pk_fma_f32 v[34:35], v[34:35], v[52:53], v[52:53] op_sel_hi:[1,0,0]
	v_rcp_f32_e32 v36, v36
	v_rcp_f32_e32 v37, v37
	v_rcp_f32_e32 v38, v38
	v_rcp_f32_e32 v39, v39
	v_rcp_f32_e32 v32, v32
	v_rcp_f32_e32 v33, v33
	v_rcp_f32_e32 v34, v34
	v_rcp_f32_e32 v35, v35
	v_pk_mul_f32 v[36:37], v[44:45], v[36:37]
	v_pk_mul_f32 v[38:39], v[46:47], v[38:39]
	v_pk_mul_f32 v[32:33], v[40:41], v[32:33]
	v_pk_mul_f32 v[34:35], v[42:43], v[34:35]
	v_cvt_pk_bf16_f32 v36, v36, v37
	v_cvt_pk_bf16_f32 v37, v38, v39
	v_cvt_pk_bf16_f32 v38, v32, v33
	v_cvt_pk_bf16_f32 v39, v34, v35
	global_store_dwordx4 v[48:49], v[36:39], off
	v_add_u32_e32 v48, 0xb0, v138
	v_mad_i64_i32 v[50:51], s[4:5], v64, s55, v[120:121]
	v_ashrrev_i32_e32 v49, 31, v48
	v_lshlrev_b64 v[34:35], 6, v[48:49]
	v_lshl_add_u64 v[34:35], s[8:9], 0, v[34:35]
	v_fmamk_f32 v32, v209, 0x3a800000, v146
	v_rsq_f32_e32 v36, v32
	v_lshl_add_u64 v[32:33], v[50:51], 0, v[122:123]
	v_mul_f32_e32 v37, 0xbfb8aa3b, v36
	v_mul_f32_e32 v36, v36, v36
	v_pk_mul_f32 v[20:21], v[20:21], v[36:37] op_sel:[0,1]
	v_pk_mul_f32 v[22:23], v[22:23], v[36:37] op_sel:[0,1]
	v_pk_mul_f32 v[16:17], v[16:17], v[36:37] op_sel:[0,1]
	v_pk_mul_f32 v[18:19], v[18:19], v[36:37] op_sel:[0,1]
	v_rcp_f32_e32 v36, v36
	v_exp_f32_e32 v20, v20
	v_exp_f32_e32 v21, v21
	v_exp_f32_e32 v22, v22
	v_exp_f32_e32 v23, v23
	v_exp_f32_e32 v16, v16
	v_exp_f32_e32 v17, v17
	v_exp_f32_e32 v18, v18
	v_exp_f32_e32 v19, v19
	v_pk_fma_f32 v[20:21], v[20:21], v[36:37], v[36:37] op_sel_hi:[1,0,0]
	v_pk_fma_f32 v[22:23], v[22:23], v[36:37], v[36:37] op_sel_hi:[1,0,0]
	v_pk_fma_f32 v[16:17], v[16:17], v[36:37], v[36:37] op_sel_hi:[1,0,0]
	v_pk_fma_f32 v[18:19], v[18:19], v[36:37], v[36:37] op_sel_hi:[1,0,0]
	v_rcp_f32_e32 v20, v20
	v_rcp_f32_e32 v21, v21
	v_rcp_f32_e32 v22, v22
	v_rcp_f32_e32 v23, v23
	v_rcp_f32_e32 v16, v16
	v_rcp_f32_e32 v17, v17
	v_rcp_f32_e32 v18, v18
	v_rcp_f32_e32 v19, v19
	v_pk_mul_f32 v[20:21], v[28:29], v[20:21]
	v_pk_mul_f32 v[22:23], v[30:31], v[22:23]
	v_pk_mul_f32 v[16:17], v[24:25], v[16:17]
	v_pk_mul_f32 v[18:19], v[26:27], v[18:19]
	v_cvt_pk_bf16_f32 v20, v20, v21
	v_cvt_pk_bf16_f32 v21, v22, v23
	v_cvt_pk_bf16_f32 v22, v16, v17
	v_cvt_pk_bf16_f32 v23, v18, v19
	global_store_dwordx4 v[32:33], v[20:23], off
	s_nop 1
	v_fmamk_f32 v16, v213, 0x3a800000, v146
	v_rsq_f32_e32 v18, v16
	v_mad_i64_i32 v[16:17], s[4:5], v48, s55, v[120:121]
	v_lshl_add_u64 v[16:17], v[16:17], 0, v[122:123]
	v_mul_f32_e32 v19, 0xbfb8aa3b, v18
	v_mul_f32_e32 v18, v18, v18
	v_pk_mul_f32 v[4:5], v[4:5], v[18:19] op_sel:[0,1]
	v_pk_mul_f32 v[6:7], v[6:7], v[18:19] op_sel:[0,1]
	v_pk_mul_f32 v[0:1], v[0:1], v[18:19] op_sel:[0,1]
	v_pk_mul_f32 v[2:3], v[2:3], v[18:19] op_sel:[0,1]
	v_rcp_f32_e32 v18, v18
	v_exp_f32_e32 v4, v4
	v_exp_f32_e32 v5, v5
	v_exp_f32_e32 v6, v6
	v_exp_f32_e32 v7, v7
	v_exp_f32_e32 v0, v0
	v_exp_f32_e32 v1, v1
	v_exp_f32_e32 v2, v2
	v_exp_f32_e32 v3, v3
	v_pk_fma_f32 v[4:5], v[4:5], v[18:19], v[18:19] op_sel_hi:[1,0,0]
	v_pk_fma_f32 v[6:7], v[6:7], v[18:19], v[18:19] op_sel_hi:[1,0,0]
	v_pk_fma_f32 v[0:1], v[0:1], v[18:19], v[18:19] op_sel_hi:[1,0,0]
	v_pk_fma_f32 v[2:3], v[2:3], v[18:19], v[18:19] op_sel_hi:[1,0,0]
	v_rcp_f32_e32 v4, v4
	v_rcp_f32_e32 v5, v5
	v_rcp_f32_e32 v6, v6
	v_rcp_f32_e32 v7, v7
	v_rcp_f32_e32 v0, v0
	v_rcp_f32_e32 v1, v1
	v_rcp_f32_e32 v2, v2
	v_rcp_f32_e32 v3, v3
	v_pk_mul_f32 v[4:5], v[12:13], v[4:5]
	v_pk_mul_f32 v[6:7], v[14:15], v[6:7]
	v_pk_mul_f32 v[0:1], v[8:9], v[0:1]
	v_pk_mul_f32 v[2:3], v[10:11], v[2:3]
	v_cvt_pk_bf16_f32 v4, v4, v5
	v_cvt_pk_bf16_f32 v5, v6, v7
	v_cvt_pk_bf16_f32 v6, v0, v1
	v_cvt_pk_bf16_f32 v7, v2, v3
	s_mov_b64 s[4:5], -1
	global_store_dwordx4 v[16:17], v[4:7], off
	s_cbranch_scc1 .LBB0_1457
	s_andn2_b64 vcc, exec, s[6:7]
	s_cbranch_vccnz .LBB0_1456
	s_barrier
	s_branch .LBB0_1456
